# deferred conversions split 1:3 between chunk and non-chunk workgroups of phase 3; w_o conversion moved to the idle tail of phase 1
# speedup vs baseline: 1.0600x; 1.0012x over previous
; #define LAS __attribute__((address_space(3)))
; __device__ __forceinline__ void transpose_item(const float* W, int N, int K, bf16_t* WT, int k0, int n0src, int n0dst, LAS float* scr, int lane) {
;     float tv[32];
; #pragma unroll
;     for (int i = 0; i < 32; ++i) tv[i] = __builtin_nontemporal_load(&W[(size_t)(k0 + 2 * i + (lane >> 5)) * N + n0src + (lane & 31)]);
; #pragma unroll
; __device__ __forceinline__ void convert_items(const Params& p, LAS float* scr, int lane, int gw, int NGW, int it_lo, int it_hi) {
;     ...
;         if (r < CV_2K) { const int kb = r / 64, nb = r % 64; transpose_item(p.in[17], 2048, 2048, (bf16_t*)(ws + WS_WO), kb * 64, nb * 32, nb * 32, scr, lane); continue; } r -= CV_2K;
.Lscopy_conv_done:
	s_mov_b64 exec, -1
	v_mbcnt_lo_u32_b32 v0, -1, 0
	v_mbcnt_hi_u32_b32 v0, -1, v0
	s_lshr_b32 s84, s24, 6
	s_sub_i32 s85, s2, 0xd5
	s_lshl_b32 s85, s85, 3
	s_add_i32 s85, s85, s84
	v_readlane_b32 s86, v254, 2
	v_readlane_b32 s87, v254, 3
	s_mul_i32 s90, s84, 0x2100
	v_lshrrev_b32_e32 v1, 5, v0
	v_and_b32_e32 v2, 31, v0
	v_mul_u32_u24_e32 v3, 0x2000, v1
	v_lshl_add_u32 v3, v2, 2, v3
	v_mul_u32_u24_e32 v4, 33, v1
	v_add_u32_e32 v4, v4, v2
	v_lshl_add_u32 v4, v4, 2, s90
	v_and_b32_e32 v5, 7, v0
	v_lshrrev_b32_e32 v6, 3, v0
	v_mul_u32_u24_e32 v7, 0x420, v5
	v_lshl_add_u32 v7, v6, 2, v7
	v_add_u32_e32 v7, s90, v7
	v_mul_u32_u24_e32 v8, 0x1000, v6
	v_lshl_add_u32 v8, v5, 4, v8
	v_add_u32_e32 v9, 0x8000, v8
	v_add_u32_e32 v10, 0x10000, v8
	v_add_u32_e32 v11, 0x18000, v8
; #define LAS __attribute__((address_space(3)))
; __device__ __forceinline__ unsigned pk2(float lo, float hi) { const f32x2_t v = {lo, hi}; const bf16x2_t b = __builtin_convertvector(v, bf16x2_t); return __builtin_bit_cast(unsigned, b); }
; #define LDS_WAIT() asm volatile("s_waitcnt lgkmcnt(0)" ::: "memory")
; __device__ __forceinline__ void transpose_item(const float* W, int N, int K, bf16_t* WT, int k0, int n0src, int n0dst, LAS float* scr, int lane) {
;     float tv[32];
; #pragma unroll
;     for (int i = 0; i < 32; ++i) tv[i] = __builtin_nontemporal_load(&W[(size_t)(k0 + 2 * i + (lane >> 5)) * N + n0src + (lane & 31)]);
; #pragma unroll
;     for (int i = 0; i < 32; ++i) scr[(2 * i + (lane >> 5)) * 33 + (lane & 31)] = tv[i];
;     LDS_WAIT();
;     const int c = lane & 7;
; #pragma unroll
;     for (int j = 0; j < 4; ++j) { const int n = (lane >> 3) + 8 * j; const LAS float* s = scr + (8 * c) * 33 + n;
;         u32x4 o; o.x = pk2(s[0 * 33], s[1 * 33]); o.y = pk2(s[2 * 33], s[3 * 33]); o.z = pk2(s[4 * 33], s[5 * 33]); o.w = pk2(s[6 * 33], s[7 * 33]);
;         *(u32x4*)(WT + (size_t)(n0dst + n) * K + k0 + 8 * c) = o; }
;     LDS_WAIT();
; }
; __device__ __forceinline__ void convert_items(const Params& p, LAS float* scr, int lane, int gw, int NGW, int it_lo, int it_hi) {
;     ...
;         if (r < CV_2K) { const int kb = r / 64, nb = r % 64; transpose_item(p.in[17], 2048, 2048, (bf16_t*)(ws + WS_WO), kb * 64, nb * 32, nb * 32, scr, lane); continue; } r -= CV_2K;
.Lgconv_wop1_loop:
	s_cmp_lt_u32 s85, 0x800
	s_cbranch_scc0 .Lgconv_wop1_done
	s_lshr_b32 s91, s85, 6
	s_mul_i32 s92, s91, 0x40
	s_sub_i32 s92, s85, s92
	s_lshl_b32 s92, s92, 5
	s_mov_b32 s95, s92
	s_mul_i32 s96, s91, 0x80000
	s_lshl_b32 s97, s92, 2
	s_add_i32 s96, s96, s97
	s_add_u32 s96, s86, s96
	s_addc_u32 s97, s87, 0
	global_load_dword v16, v3, s[96:97] nt
	s_add_u32 s96, s96, 0x4000
	s_addc_u32 s97, s97, 0
	global_load_dword v17, v3, s[96:97] nt
	s_add_u32 s96, s96, 0x4000
	s_addc_u32 s97, s97, 0
	global_load_dword v18, v3, s[96:97] nt
	s_add_u32 s96, s96, 0x4000
	s_addc_u32 s97, s97, 0
	global_load_dword v19, v3, s[96:97] nt
	s_add_u32 s96, s96, 0x4000
	s_addc_u32 s97, s97, 0
	global_load_dword v20, v3, s[96:97] nt
	s_add_u32 s96, s96, 0x4000
	s_addc_u32 s97, s97, 0
	global_load_dword v21, v3, s[96:97] nt
	s_add_u32 s96, s96, 0x4000
	s_addc_u32 s97, s97, 0
	global_load_dword v22, v3, s[96:97] nt
	s_add_u32 s96, s96, 0x4000
	s_addc_u32 s97, s97, 0
	global_load_dword v23, v3, s[96:97] nt
	s_add_u32 s96, s96, 0x4000
	s_addc_u32 s97, s97, 0
	global_load_dword v24, v3, s[96:97] nt
	s_add_u32 s96, s96, 0x4000
	s_addc_u32 s97, s97, 0
	global_load_dword v25, v3, s[96:97] nt
	s_add_u32 s96, s96, 0x4000
	s_addc_u32 s97, s97, 0
	global_load_dword v26, v3, s[96:97] nt
	s_add_u32 s96, s96, 0x4000
	s_addc_u32 s97, s97, 0
	global_load_dword v27, v3, s[96:97] nt
	s_add_u32 s96, s96, 0x4000
	s_addc_u32 s97, s97, 0
	global_load_dword v28, v3, s[96:97] nt
	s_add_u32 s96, s96, 0x4000
	s_addc_u32 s97, s97, 0
	global_load_dword v29, v3, s[96:97] nt
	s_add_u32 s96, s96, 0x4000
	s_addc_u32 s97, s97, 0
	global_load_dword v30, v3, s[96:97] nt
	s_add_u32 s96, s96, 0x4000
	s_addc_u32 s97, s97, 0
	global_load_dword v31, v3, s[96:97] nt
	s_add_u32 s96, s96, 0x4000
	s_addc_u32 s97, s97, 0
	global_load_dword v32, v3, s[96:97] nt
	s_add_u32 s96, s96, 0x4000
	s_addc_u32 s97, s97, 0
	global_load_dword v33, v3, s[96:97] nt
	s_add_u32 s96, s96, 0x4000
	s_addc_u32 s97, s97, 0
	global_load_dword v34, v3, s[96:97] nt
	s_add_u32 s96, s96, 0x4000
	s_addc_u32 s97, s97, 0
	global_load_dword v35, v3, s[96:97] nt
	s_add_u32 s96, s96, 0x4000
	s_addc_u32 s97, s97, 0
	global_load_dword v36, v3, s[96:97] nt
	s_add_u32 s96, s96, 0x4000
	s_addc_u32 s97, s97, 0
	global_load_dword v37, v3, s[96:97] nt
	s_add_u32 s96, s96, 0x4000
	s_addc_u32 s97, s97, 0
	global_load_dword v38, v3, s[96:97] nt
	s_add_u32 s96, s96, 0x4000
	s_addc_u32 s97, s97, 0
	global_load_dword v39, v3, s[96:97] nt
	s_add_u32 s96, s96, 0x4000
	s_addc_u32 s97, s97, 0
	global_load_dword v40, v3, s[96:97] nt
	s_add_u32 s96, s96, 0x4000
	s_addc_u32 s97, s97, 0
	global_load_dword v41, v3, s[96:97] nt
	s_add_u32 s96, s96, 0x4000
	s_addc_u32 s97, s97, 0
	global_load_dword v42, v3, s[96:97] nt
	s_add_u32 s96, s96, 0x4000
	s_addc_u32 s97, s97, 0
	global_load_dword v43, v3, s[96:97] nt
	s_add_u32 s96, s96, 0x4000
	s_addc_u32 s97, s97, 0
	global_load_dword v44, v3, s[96:97] nt
	s_add_u32 s96, s96, 0x4000
	s_addc_u32 s97, s97, 0
	global_load_dword v45, v3, s[96:97] nt
	s_add_u32 s96, s96, 0x4000
	s_addc_u32 s97, s97, 0
	global_load_dword v46, v3, s[96:97] nt
	s_add_u32 s96, s96, 0x4000
	s_addc_u32 s97, s97, 0
	global_load_dword v47, v3, s[96:97] nt
	s_mul_i32 s92, s95, 0x1000
	s_lshl_b32 s93, s91, 7
	s_add_i32 s92, s92, s93
	s_add_u32 s92, s22, s92
	s_addc_u32 s93, s23, 0
	s_add_u32 s92, s92, 0xc80000
	s_addc_u32 s93, s93, 0
	s_waitcnt vmcnt(31)
	ds_write_b32 v4, v16
	s_waitcnt vmcnt(30)
	ds_write_b32 v4, v17 offset:264
	s_waitcnt vmcnt(29)
	ds_write_b32 v4, v18 offset:528
	s_waitcnt vmcnt(28)
	ds_write_b32 v4, v19 offset:792
	s_waitcnt vmcnt(27)
	ds_write_b32 v4, v20 offset:1056
	s_waitcnt vmcnt(26)
	ds_write_b32 v4, v21 offset:1320
	s_waitcnt vmcnt(25)
	ds_write_b32 v4, v22 offset:1584
	s_waitcnt vmcnt(24)
	ds_write_b32 v4, v23 offset:1848
	s_waitcnt vmcnt(23)
	ds_write_b32 v4, v24 offset:2112
	s_waitcnt vmcnt(22)
	ds_write_b32 v4, v25 offset:2376
	s_waitcnt vmcnt(21)
	ds_write_b32 v4, v26 offset:2640
	s_waitcnt vmcnt(20)
	ds_write_b32 v4, v27 offset:2904
	s_waitcnt vmcnt(19)
	ds_write_b32 v4, v28 offset:3168
	s_waitcnt vmcnt(18)
	ds_write_b32 v4, v29 offset:3432
	s_waitcnt vmcnt(17)
	ds_write_b32 v4, v30 offset:3696
	s_waitcnt vmcnt(16)
	ds_write_b32 v4, v31 offset:3960
	s_waitcnt vmcnt(15)
	ds_write_b32 v4, v32 offset:4224
	s_waitcnt vmcnt(14)
	ds_write_b32 v4, v33 offset:4488
	s_waitcnt vmcnt(13)
	ds_write_b32 v4, v34 offset:4752
	s_waitcnt vmcnt(12)
	ds_write_b32 v4, v35 offset:5016
	s_waitcnt vmcnt(11)
	ds_write_b32 v4, v36 offset:5280
	s_waitcnt vmcnt(10)
	ds_write_b32 v4, v37 offset:5544
	s_waitcnt vmcnt(9)
	ds_write_b32 v4, v38 offset:5808
	s_waitcnt vmcnt(8)
	ds_write_b32 v4, v39 offset:6072
	s_waitcnt vmcnt(7)
	ds_write_b32 v4, v40 offset:6336
	s_waitcnt vmcnt(6)
	ds_write_b32 v4, v41 offset:6600
	s_waitcnt vmcnt(5)
	ds_write_b32 v4, v42 offset:6864
	s_waitcnt vmcnt(4)
	ds_write_b32 v4, v43 offset:7128
	s_waitcnt vmcnt(3)
	ds_write_b32 v4, v44 offset:7392
	s_waitcnt vmcnt(2)
	ds_write_b32 v4, v45 offset:7656
	s_waitcnt vmcnt(1)
	ds_write_b32 v4, v46 offset:7920
	s_waitcnt vmcnt(0)
	ds_write_b32 v4, v47 offset:8184
	s_waitcnt lgkmcnt(0)
	ds_read_b32 v48, v7
	ds_read_b32 v49, v7 offset:132
	ds_read_b32 v50, v7 offset:264
	ds_read_b32 v51, v7 offset:396
	ds_read_b32 v52, v7 offset:528
	ds_read_b32 v53, v7 offset:660
	ds_read_b32 v54, v7 offset:792
	ds_read_b32 v55, v7 offset:924
	s_waitcnt lgkmcnt(0)
	v_cvt_pk_bf16_f32 v80, v48, v49
	v_cvt_pk_bf16_f32 v81, v50, v51
	v_cvt_pk_bf16_f32 v82, v52, v53
	v_cvt_pk_bf16_f32 v83, v54, v55
	global_store_dwordx4 v8, v[80:83], s[92:93]
	ds_read_b32 v56, v7 offset:32
	ds_read_b32 v57, v7 offset:164
	ds_read_b32 v58, v7 offset:296
	ds_read_b32 v59, v7 offset:428
	ds_read_b32 v60, v7 offset:560
	ds_read_b32 v61, v7 offset:692
	ds_read_b32 v62, v7 offset:824
	ds_read_b32 v63, v7 offset:956
	s_waitcnt lgkmcnt(0)
	v_cvt_pk_bf16_f32 v84, v56, v57
	v_cvt_pk_bf16_f32 v85, v58, v59
	v_cvt_pk_bf16_f32 v86, v60, v61
	v_cvt_pk_bf16_f32 v87, v62, v63
	global_store_dwordx4 v9, v[84:87], s[92:93]
	ds_read_b32 v64, v7 offset:64
	ds_read_b32 v65, v7 offset:196
	ds_read_b32 v66, v7 offset:328
	ds_read_b32 v67, v7 offset:460
	ds_read_b32 v68, v7 offset:592
	ds_read_b32 v69, v7 offset:724
	ds_read_b32 v70, v7 offset:856
	ds_read_b32 v71, v7 offset:988
	s_waitcnt lgkmcnt(0)
	v_cvt_pk_bf16_f32 v88, v64, v65
	v_cvt_pk_bf16_f32 v89, v66, v67
	v_cvt_pk_bf16_f32 v90, v68, v69
	v_cvt_pk_bf16_f32 v91, v70, v71
	global_store_dwordx4 v10, v[88:91], s[92:93]
	ds_read_b32 v72, v7 offset:96
	ds_read_b32 v73, v7 offset:228
	ds_read_b32 v74, v7 offset:360
	ds_read_b32 v75, v7 offset:492
	ds_read_b32 v76, v7 offset:624
	ds_read_b32 v77, v7 offset:756
	ds_read_b32 v78, v7 offset:888
	ds_read_b32 v79, v7 offset:1020
	s_waitcnt lgkmcnt(0)
	v_cvt_pk_bf16_f32 v92, v72, v73
	v_cvt_pk_bf16_f32 v93, v74, v75
	v_cvt_pk_bf16_f32 v94, v76, v77
	v_cvt_pk_bf16_f32 v95, v78, v79
	global_store_dwordx4 v11, v[92:95], s[92:93]
	s_add_i32 s85, s85, 0x158
	s_branch .Lgconv_wop1_loop

; #define LAS __attribute__((address_space(3)))
; __device__ __forceinline__ void transpose_item(const float* W, int N, int K, bf16_t* WT, int k0, int n0src, int n0dst, LAS float* scr, int lane) {
;     float tv[32];
; #pragma unroll
;     for (int i = 0; i < 32; ++i) tv[i] = __builtin_nontemporal_load(&W[(size_t)(k0 + 2 * i + (lane >> 5)) * N + n0src + (lane & 31)]);
; __device__ __forceinline__ void convert_items(const Params& p, LAS float* scr, int lane, int gw, int NGW, int it_lo, int it_hi) {
;     ...
;     for (int it = it_lo + gw; it < it_hi; it += NGW) {
;         int r = it;
;         if (r < CV_WIN) { const int kb = r / 417, nb = r % 417, ns = nb * 32; const int nd = ns < 9216 ? ns : (ns < 9248 ? 13312 + (ns - 9216) : ns - 32);
;             transpose_item(p.in[8], IN_COLS, 2048, (bf16_t*)(ws + WS_WIN), kb * 64, ns, nd, scr, lane); continue; } r -= CV_WIN;
;         if (r < CV_POOL) { const int g = r / 32, q = r % 32, kb = q / 8, nb = q % 8;
;             transpose_item(p.in[9] + g * 65536, 256, 256, (bf16_t*)(ws + WS_WPOOL) + g * 65536, kb * 64, nb * 32, nb * 32, scr, lane); continue; } r -= CV_POOL;
;         if (r < CV_WPU) { const int kb = r / 64, nb = r % 64; transpose_item(p.in[15], 2048, 1024, (bf16_t*)(ws + WS_WPU), kb * 64, nb * 32, nb * 32, scr, lane); continue; } r -= CV_WPU;
;         if (r < CV_2K) { const int kb = r / 64, nb = r % 64; transpose_item(p.in[16], 2048, 2048, (bf16_t*)(ws + WS_WGU), kb * 64, nb * 32, nb * 32, scr, lane); continue; } r -= CV_2K;
;         if (r < CV_2K) { const int kb = r / 64, nb = r % 64; transpose_item(p.in[17], 2048, 2048, (bf16_t*)(ws + WS_WO), kb * 64, nb * 32, nb * 32, scr, lane); continue; } r -= CV_2K;
;         if (r < CV_GATE) { const int kb = r / 352, nb = r % 352, ns = nb * 32; int nd; if (ns < DFF) nd = 256 * (ns / 128) + (ns % 128); else { const int j = ns - DFF; nd = 256 * (j / 128) + 128 + (j % 128); }
;             transpose_item(p.in[19], 2 * DFF, 2048, (bf16_t*)(ws + WS_WGATE), kb * 64, ns, nd, scr, lane); continue; } r -= CV_GATE;
.LBB0_896:
	s_or_b64 exec, exec, s[0:1]
	s_mov_b64 exec, -1
	v_mbcnt_lo_u32_b32 v0, -1, 0
	v_mbcnt_hi_u32_b32 v0, -1, v0
	s_lshr_b32 s84, s24, 6
	s_cmp_gt_u32 s2, 0xbf
	s_cbranch_scc1 .Lgconv_gate_hi
	s_sub_i32 s85, s2, 64
	s_lshl_b32 s85, s85, 3
	s_add_i32 s85, s85, s84
	s_mul_i32 s88, s85, 1
	s_add_i32 s89, s88, 1
	s_branch .Lgconv_gate_slots
.Lgconv_gate_hi:
	s_sub_i32 s85, s2, 0xc0
	s_lshl_b32 s85, s85, 3
	s_add_i32 s85, s85, s84
	s_mul_i32 s88, s85, 3
	s_add_i32 s88, s88, 0x400
	s_add_i32 s89, s88, 3
.Lgconv_gate_slots:
	s_add_i32 s85, s88, 0x0
	s_sub_i32 s91, s85, 0xa00
	s_cmp_ge_u32 s85, 0xa00
	s_cselect_b32 s85, s91, s85
	v_readlane_b32 s86, v254, 6
	v_readlane_b32 s87, v254, 7
	s_mul_i32 s90, s84, 0x2100
	v_lshrrev_b32_e32 v1, 5, v0
	v_and_b32_e32 v2, 31, v0
	v_mul_u32_u24_e32 v3, 0xb000, v1
	v_lshl_add_u32 v3, v2, 2, v3
	v_mul_u32_u24_e32 v4, 33, v1
	v_add_u32_e32 v4, v4, v2
	v_lshl_add_u32 v4, v4, 2, s90
	v_and_b32_e32 v5, 7, v0
	v_lshrrev_b32_e32 v6, 3, v0
	v_mul_u32_u24_e32 v7, 0x420, v5
	v_lshl_add_u32 v7, v6, 2, v7
	v_add_u32_e32 v7, s90, v7
	v_mul_u32_u24_e32 v8, 0x1000, v6
	v_lshl_add_u32 v8, v5, 4, v8
	v_add_u32_e32 v9, 0x8000, v8
	v_add_u32_e32 v10, 0x10000, v8
	v_add_u32_e32 v11, 0x18000, v8
.Lgconv_gate_loop:
	s_cmp_lt_u32 s85, 0x2c00
	s_cbranch_scc0 .Lgconv_gate_next
	s_mul_i32 s91, s85, 0xba2f
	s_lshr_b32 s91, s91, 24
	s_mul_i32 s92, s91, 0x160
	s_sub_i32 s92, s85, s92
	s_lshl_b32 s92, s92, 5
	s_cmp_lt_u32 s92, 0x1600
	s_cselect_b32 s93, 0, 0x1600
	s_cselect_b32 s94, 0, 0x80
	s_sub_i32 s93, s92, s93
	s_lshr_b32 s95, s93, 7
	s_lshl_b32 s95, s95, 8
	s_and_b32 s93, s93, 0x7f
	s_add_i32 s95, s95, s93
	s_add_i32 s95, s95, s94
	s_mul_i32 s96, s91, 0x2c0000
	s_lshl_b32 s97, s92, 2
	s_add_i32 s96, s96, s97
	s_add_u32 s96, s86, s96
	s_addc_u32 s97, s87, 0
	global_load_dword v16, v3, s[96:97] nt
	s_add_u32 s96, s96, 0x16000
	s_addc_u32 s97, s97, 0
	global_load_dword v17, v3, s[96:97] nt
	s_add_u32 s96, s96, 0x16000
	s_addc_u32 s97, s97, 0
	global_load_dword v18, v3, s[96:97] nt
	s_add_u32 s96, s96, 0x16000
	s_addc_u32 s97, s97, 0
	global_load_dword v19, v3, s[96:97] nt
	s_add_u32 s96, s96, 0x16000
	s_addc_u32 s97, s97, 0
	global_load_dword v20, v3, s[96:97] nt
	s_add_u32 s96, s96, 0x16000
	s_addc_u32 s97, s97, 0
	global_load_dword v21, v3, s[96:97] nt
	s_add_u32 s96, s96, 0x16000
	s_addc_u32 s97, s97, 0
	global_load_dword v22, v3, s[96:97] nt
	s_add_u32 s96, s96, 0x16000
	s_addc_u32 s97, s97, 0
	global_load_dword v23, v3, s[96:97] nt
	s_add_u32 s96, s96, 0x16000
	s_addc_u32 s97, s97, 0
	global_load_dword v24, v3, s[96:97] nt
	s_add_u32 s96, s96, 0x16000
	s_addc_u32 s97, s97, 0
	global_load_dword v25, v3, s[96:97] nt
	s_add_u32 s96, s96, 0x16000
	s_addc_u32 s97, s97, 0
	global_load_dword v26, v3, s[96:97] nt
	s_add_u32 s96, s96, 0x16000
	s_addc_u32 s97, s97, 0
	global_load_dword v27, v3, s[96:97] nt
	s_add_u32 s96, s96, 0x16000
	s_addc_u32 s97, s97, 0
	global_load_dword v28, v3, s[96:97] nt
	s_add_u32 s96, s96, 0x16000
	s_addc_u32 s97, s97, 0
	global_load_dword v29, v3, s[96:97] nt
	s_add_u32 s96, s96, 0x16000
	s_addc_u32 s97, s97, 0
	global_load_dword v30, v3, s[96:97] nt
	s_add_u32 s96, s96, 0x16000
	s_addc_u32 s97, s97, 0
	global_load_dword v31, v3, s[96:97] nt
	s_add_u32 s96, s96, 0x16000
	s_addc_u32 s97, s97, 0
	global_load_dword v32, v3, s[96:97] nt
	s_add_u32 s96, s96, 0x16000
	s_addc_u32 s97, s97, 0
	global_load_dword v33, v3, s[96:97] nt
	s_add_u32 s96, s96, 0x16000
	s_addc_u32 s97, s97, 0
	global_load_dword v34, v3, s[96:97] nt
	s_add_u32 s96, s96, 0x16000
	s_addc_u32 s97, s97, 0
	global_load_dword v35, v3, s[96:97] nt
	s_add_u32 s96, s96, 0x16000
	s_addc_u32 s97, s97, 0
	global_load_dword v36, v3, s[96:97] nt
	s_add_u32 s96, s96, 0x16000
	s_addc_u32 s97, s97, 0
	global_load_dword v37, v3, s[96:97] nt
	s_add_u32 s96, s96, 0x16000
	s_addc_u32 s97, s97, 0
	global_load_dword v38, v3, s[96:97] nt
	s_add_u32 s96, s96, 0x16000
	s_addc_u32 s97, s97, 0
	global_load_dword v39, v3, s[96:97] nt
	s_add_u32 s96, s96, 0x16000
	s_addc_u32 s97, s97, 0
	global_load_dword v40, v3, s[96:97] nt
	s_add_u32 s96, s96, 0x16000
	s_addc_u32 s97, s97, 0
	global_load_dword v41, v3, s[96:97] nt
	s_add_u32 s96, s96, 0x16000
	s_addc_u32 s97, s97, 0
	global_load_dword v42, v3, s[96:97] nt
	s_add_u32 s96, s96, 0x16000
	s_addc_u32 s97, s97, 0
	global_load_dword v43, v3, s[96:97] nt
	s_add_u32 s96, s96, 0x16000
	s_addc_u32 s97, s97, 0
	global_load_dword v44, v3, s[96:97] nt
	s_add_u32 s96, s96, 0x16000
	s_addc_u32 s97, s97, 0
	global_load_dword v45, v3, s[96:97] nt
	s_add_u32 s96, s96, 0x16000
	s_addc_u32 s97, s97, 0
	global_load_dword v46, v3, s[96:97] nt
	s_add_u32 s96, s96, 0x16000
	s_addc_u32 s97, s97, 0
	global_load_dword v47, v3, s[96:97] nt
	s_mul_i32 s92, s95, 0x1000
	s_lshl_b32 s93, s91, 7
	s_add_i32 s92, s92, s93
	s_add_u32 s92, s22, s92
	s_addc_u32 s93, s23, 0
	s_add_u32 s92, s92, 0x1480000
	s_addc_u32 s93, s93, 0
	s_waitcnt vmcnt(31)
; #define LAS __attribute__((address_space(3)))
; __device__ __forceinline__ unsigned pk2(float lo, float hi) { const f32x2_t v = {lo, hi}; const bf16x2_t b = __builtin_convertvector(v, bf16x2_t); return __builtin_bit_cast(unsigned, b); }
; #define LDS_WAIT() asm volatile("s_waitcnt lgkmcnt(0)" ::: "memory")
; __device__ __forceinline__ void transpose_item(const float* W, int N, int K, bf16_t* WT, int k0, int n0src, int n0dst, LAS float* scr, int lane) {
;     ...
; #pragma unroll
;     for (int i = 0; i < 32; ++i) scr[(2 * i + (lane >> 5)) * 33 + (lane & 31)] = tv[i];
;     LDS_WAIT();
;     const int c = lane & 7;
; #pragma unroll
;     for (int j = 0; j < 4; ++j) { const int n = (lane >> 3) + 8 * j; const LAS float* s = scr + (8 * c) * 33 + n;
;         u32x4 o; o.x = pk2(s[0 * 33], s[1 * 33]); o.y = pk2(s[2 * 33], s[3 * 33]); o.z = pk2(s[4 * 33], s[5 * 33]); o.w = pk2(s[6 * 33], s[7 * 33]);
;         *(u32x4*)(WT + (size_t)(n0dst + n) * K + k0 + 8 * c) = o; }
;     LDS_WAIT();
	ds_write_b32 v4, v16
	s_waitcnt vmcnt(30)
	ds_write_b32 v4, v17 offset:264
	s_waitcnt vmcnt(29)
	ds_write_b32 v4, v18 offset:528
	s_waitcnt vmcnt(28)
	ds_write_b32 v4, v19 offset:792
	s_waitcnt vmcnt(27)
	ds_write_b32 v4, v20 offset:1056
	s_waitcnt vmcnt(26)
	ds_write_b32 v4, v21 offset:1320
	s_waitcnt vmcnt(25)
	ds_write_b32 v4, v22 offset:1584
	s_waitcnt vmcnt(24)
	ds_write_b32 v4, v23 offset:1848
	s_waitcnt vmcnt(23)
	ds_write_b32 v4, v24 offset:2112
	s_waitcnt vmcnt(22)
	ds_write_b32 v4, v25 offset:2376
	s_waitcnt vmcnt(21)
	ds_write_b32 v4, v26 offset:2640
	s_waitcnt vmcnt(20)
	ds_write_b32 v4, v27 offset:2904
	s_waitcnt vmcnt(19)
	ds_write_b32 v4, v28 offset:3168
	s_waitcnt vmcnt(18)
	ds_write_b32 v4, v29 offset:3432
	s_waitcnt vmcnt(17)
	ds_write_b32 v4, v30 offset:3696
	s_waitcnt vmcnt(16)
	ds_write_b32 v4, v31 offset:3960
	s_waitcnt vmcnt(15)
	ds_write_b32 v4, v32 offset:4224
	s_waitcnt vmcnt(14)
	ds_write_b32 v4, v33 offset:4488
	s_waitcnt vmcnt(13)
	ds_write_b32 v4, v34 offset:4752
	s_waitcnt vmcnt(12)
	ds_write_b32 v4, v35 offset:5016
	s_waitcnt vmcnt(11)
	ds_write_b32 v4, v36 offset:5280
	s_waitcnt vmcnt(10)
	ds_write_b32 v4, v37 offset:5544
	s_waitcnt vmcnt(9)
	ds_write_b32 v4, v38 offset:5808
	s_waitcnt vmcnt(8)
	ds_write_b32 v4, v39 offset:6072
	s_waitcnt vmcnt(7)
	ds_write_b32 v4, v40 offset:6336
	s_waitcnt vmcnt(6)
	ds_write_b32 v4, v41 offset:6600
	s_waitcnt vmcnt(5)
	ds_write_b32 v4, v42 offset:6864
	s_waitcnt vmcnt(4)
	ds_write_b32 v4, v43 offset:7128
	s_waitcnt vmcnt(3)
	ds_write_b32 v4, v44 offset:7392
	s_waitcnt vmcnt(2)
	ds_write_b32 v4, v45 offset:7656
	s_waitcnt vmcnt(1)
	ds_write_b32 v4, v46 offset:7920
	s_waitcnt vmcnt(0)
	ds_write_b32 v4, v47 offset:8184
	s_waitcnt lgkmcnt(0)
	ds_read_b32 v48, v7
	ds_read_b32 v49, v7 offset:132
	ds_read_b32 v50, v7 offset:264
	ds_read_b32 v51, v7 offset:396
	ds_read_b32 v52, v7 offset:528
	ds_read_b32 v53, v7 offset:660
	ds_read_b32 v54, v7 offset:792
	ds_read_b32 v55, v7 offset:924
	s_waitcnt lgkmcnt(0)
	v_cvt_pk_bf16_f32 v80, v48, v49
	v_cvt_pk_bf16_f32 v81, v50, v51
	v_cvt_pk_bf16_f32 v82, v52, v53
	v_cvt_pk_bf16_f32 v83, v54, v55
	global_store_dwordx4 v8, v[80:83], s[92:93]
	ds_read_b32 v56, v7 offset:32
	ds_read_b32 v57, v7 offset:164
	ds_read_b32 v58, v7 offset:296
	ds_read_b32 v59, v7 offset:428
	ds_read_b32 v60, v7 offset:560
	ds_read_b32 v61, v7 offset:692
	ds_read_b32 v62, v7 offset:824
	ds_read_b32 v63, v7 offset:956
	s_waitcnt lgkmcnt(0)
	v_cvt_pk_bf16_f32 v84, v56, v57
	v_cvt_pk_bf16_f32 v85, v58, v59
	v_cvt_pk_bf16_f32 v86, v60, v61
	v_cvt_pk_bf16_f32 v87, v62, v63
	global_store_dwordx4 v9, v[84:87], s[92:93]
	ds_read_b32 v64, v7 offset:64
	ds_read_b32 v65, v7 offset:196
	ds_read_b32 v66, v7 offset:328
	ds_read_b32 v67, v7 offset:460
	ds_read_b32 v68, v7 offset:592
	ds_read_b32 v69, v7 offset:724
	ds_read_b32 v70, v7 offset:856
	ds_read_b32 v71, v7 offset:988
	s_waitcnt lgkmcnt(0)
	v_cvt_pk_bf16_f32 v88, v64, v65
	v_cvt_pk_bf16_f32 v89, v66, v67
	v_cvt_pk_bf16_f32 v90, v68, v69
	v_cvt_pk_bf16_f32 v91, v70, v71
	global_store_dwordx4 v10, v[88:91], s[92:93]
	ds_read_b32 v72, v7 offset:96
	ds_read_b32 v73, v7 offset:228
	ds_read_b32 v74, v7 offset:360
	ds_read_b32 v75, v7 offset:492
	ds_read_b32 v76, v7 offset:624
	ds_read_b32 v77, v7 offset:756
	ds_read_b32 v78, v7 offset:888
	ds_read_b32 v79, v7 offset:1020
	s_waitcnt lgkmcnt(0)
	v_cvt_pk_bf16_f32 v92, v72, v73
	v_cvt_pk_bf16_f32 v93, v74, v75
	v_cvt_pk_bf16_f32 v94, v76, v77
	v_cvt_pk_bf16_f32 v95, v78, v79
	global_store_dwordx4 v11, v[92:95], s[92:93]
	s_add_i32 s85, s85, 0xa00
	s_branch .Lgconv_gate_loop

; __device__ __forceinline__ void convert_items(const Params& p, LAS float* scr, int lane, int gw, int NGW, int it_lo, int it_hi) {
;     ...
;     for (int it = it_lo + gw; it < it_hi; it += NGW) {
;         int r = it;
;         if (r < CV_WIN) { const int kb = r / 417, nb = r % 417, ns = nb * 32; const int nd = ns < 9216 ? ns : (ns < 9248 ? 13312 + (ns - 9216) : ns - 32);
;             transpose_item(p.in[8], IN_COLS, 2048, (bf16_t*)(ws + WS_WIN), kb * 64, ns, nd, scr, lane); continue; } r -= CV_WIN;
;         if (r < CV_POOL) { const int g = r / 32, q = r % 32, kb = q / 8, nb = q % 8;
;             transpose_item(p.in[9] + g * 65536, 256, 256, (bf16_t*)(ws + WS_WPOOL) + g * 65536, kb * 64, nb * 32, nb * 32, scr, lane); continue; } r -= CV_POOL;
;         if (r < CV_WPU) { const int kb = r / 64, nb = r % 64; transpose_item(p.in[15], 2048, 1024, (bf16_t*)(ws + WS_WPU), kb * 64, nb * 32, nb * 32, scr, lane); continue; } r -= CV_WPU;
;         if (r < CV_2K) { const int kb = r / 64, nb = r % 64; transpose_item(p.in[16], 2048, 2048, (bf16_t*)(ws + WS_WGU), kb * 64, nb * 32, nb * 32, scr, lane); continue; } r -= CV_2K;
;         if (r < CV_2K) { const int kb = r / 64, nb = r % 64; transpose_item(p.in[17], 2048, 2048, (bf16_t*)(ws + WS_WO), kb * 64, nb * 32, nb * 32, scr, lane); continue; } r -= CV_2K;
.Lgconv_gate_done:
	s_branch .Lgconv_wo_done
	s_mov_b64 exec, -1
	v_mbcnt_lo_u32_b32 v0, -1, 0
	v_mbcnt_hi_u32_b32 v0, -1, v0
	s_lshr_b32 s84, s24, 6
	s_cmp_gt_u32 s2, 0xbf
	s_cbranch_scc1 .Lgconv_wo_hi
	s_sub_i32 s85, s2, 64
	s_lshl_b32 s85, s85, 3
	s_add_i32 s85, s85, s84
	s_mul_i32 s88, s85, 1
	s_add_i32 s89, s88, 1
	s_branch .Lgconv_wo_slots

; #define LAS __attribute__((address_space(3)))
; __device__ __forceinline__ unsigned pk2(float lo, float hi) { const f32x2_t v = {lo, hi}; const bf16x2_t b = __builtin_convertvector(v, bf16x2_t); return __builtin_bit_cast(unsigned, b); }
; #define LDS_WAIT() asm volatile("s_waitcnt lgkmcnt(0)" ::: "memory")
; __device__ __forceinline__ void transpose_item(const float* W, int N, int K, bf16_t* WT, int k0, int n0src, int n0dst, LAS float* scr, int lane) {
;     float tv[32];
; #pragma unroll
;     for (int i = 0; i < 32; ++i) tv[i] = __builtin_nontemporal_load(&W[(size_t)(k0 + 2 * i + (lane >> 5)) * N + n0src + (lane & 31)]);
; #pragma unroll
;     for (int i = 0; i < 32; ++i) scr[(2 * i + (lane >> 5)) * 33 + (lane & 31)] = tv[i];
;     LDS_WAIT();
;     const int c = lane & 7;
; #pragma unroll
;     for (int j = 0; j < 4; ++j) { const int n = (lane >> 3) + 8 * j; const LAS float* s = scr + (8 * c) * 33 + n;
;         u32x4 o; o.x = pk2(s[0 * 33], s[1 * 33]); o.y = pk2(s[2 * 33], s[3 * 33]); o.z = pk2(s[4 * 33], s[5 * 33]); o.w = pk2(s[6 * 33], s[7 * 33]);
;         *(u32x4*)(WT + (size_t)(n0dst + n) * K + k0 + 8 * c) = o; }
; __device__ __forceinline__ void convert_items(const Params& p, LAS float* scr, int lane, int gw, int NGW, int it_lo, int it_hi) {
;     ...
;         if (r < CV_2K) { const int kb = r / 64, nb = r % 64; transpose_item(p.in[17], 2048, 2048, (bf16_t*)(ws + WS_WO), kb * 64, nb * 32, nb * 32, scr, lane); continue; } r -= CV_2K;
.Lgconv_wo_slots:
	s_add_i32 s85, s88, 0x600
	s_sub_i32 s91, s85, 0xa00
	s_cmp_ge_u32 s85, 0xa00
	s_cselect_b32 s85, s91, s85
	v_readlane_b32 s86, v254, 2
	v_readlane_b32 s87, v254, 3
	s_mul_i32 s90, s84, 0x2100
	v_lshrrev_b32_e32 v1, 5, v0
	v_and_b32_e32 v2, 31, v0
	v_mul_u32_u24_e32 v3, 0x2000, v1
	v_lshl_add_u32 v3, v2, 2, v3
	v_mul_u32_u24_e32 v4, 33, v1
	v_add_u32_e32 v4, v4, v2
	v_lshl_add_u32 v4, v4, 2, s90
	v_and_b32_e32 v5, 7, v0
	v_lshrrev_b32_e32 v6, 3, v0
	v_mul_u32_u24_e32 v7, 0x420, v5
	v_lshl_add_u32 v7, v6, 2, v7
	v_add_u32_e32 v7, s90, v7
	v_mul_u32_u24_e32 v8, 0x1000, v6
	v_lshl_add_u32 v8, v5, 4, v8
	v_add_u32_e32 v9, 0x8000, v8
	v_add_u32_e32 v10, 0x10000, v8
	v_add_u32_e32 v11, 0x18000, v8
; #define LAS __attribute__((address_space(3)))
; __device__ __forceinline__ unsigned pk2(float lo, float hi) { const f32x2_t v = {lo, hi}; const bf16x2_t b = __builtin_convertvector(v, bf16x2_t); return __builtin_bit_cast(unsigned, b); }
; #define LDS_WAIT() asm volatile("s_waitcnt lgkmcnt(0)" ::: "memory")
; __device__ __forceinline__ void transpose_item(const float* W, int N, int K, bf16_t* WT, int k0, int n0src, int n0dst, LAS float* scr, int lane) {
;     float tv[32];
; #pragma unroll
;     for (int i = 0; i < 32; ++i) tv[i] = __builtin_nontemporal_load(&W[(size_t)(k0 + 2 * i + (lane >> 5)) * N + n0src + (lane & 31)]);
; #pragma unroll
;     for (int i = 0; i < 32; ++i) scr[(2 * i + (lane >> 5)) * 33 + (lane & 31)] = tv[i];
;     LDS_WAIT();
;     const int c = lane & 7;
; #pragma unroll
;     for (int j = 0; j < 4; ++j) { const int n = (lane >> 3) + 8 * j; const LAS float* s = scr + (8 * c) * 33 + n;
;         u32x4 o; o.x = pk2(s[0 * 33], s[1 * 33]); o.y = pk2(s[2 * 33], s[3 * 33]); o.z = pk2(s[4 * 33], s[5 * 33]); o.w = pk2(s[6 * 33], s[7 * 33]);
;         *(u32x4*)(WT + (size_t)(n0dst + n) * K + k0 + 8 * c) = o; }
;     LDS_WAIT();
; __device__ __forceinline__ void convert_items(const Params& p, LAS float* scr, int lane, int gw, int NGW, int it_lo, int it_hi) {
;     ...
;         if (r < CV_2K) { const int kb = r / 64, nb = r % 64; transpose_item(p.in[17], 2048, 2048, (bf16_t*)(ws + WS_WO), kb * 64, nb * 32, nb * 32, scr, lane); continue; } r -= CV_2K;
.Lgconv_wo_loop:
	s_cmp_lt_u32 s85, 0x800
	s_cbranch_scc0 .Lgconv_wo_next
	s_lshr_b32 s91, s85, 6
	s_mul_i32 s92, s91, 0x40
	s_sub_i32 s92, s85, s92
	s_lshl_b32 s92, s92, 5
	s_mov_b32 s95, s92
	s_mul_i32 s96, s91, 0x80000
	s_lshl_b32 s97, s92, 2
	s_add_i32 s96, s96, s97
	s_add_u32 s96, s86, s96
	s_addc_u32 s97, s87, 0
	global_load_dword v16, v3, s[96:97] nt
	s_add_u32 s96, s96, 0x4000
	s_addc_u32 s97, s97, 0
	global_load_dword v17, v3, s[96:97] nt
	s_add_u32 s96, s96, 0x4000
	s_addc_u32 s97, s97, 0
	global_load_dword v18, v3, s[96:97] nt
	s_add_u32 s96, s96, 0x4000
	s_addc_u32 s97, s97, 0
	global_load_dword v19, v3, s[96:97] nt
	s_add_u32 s96, s96, 0x4000
	s_addc_u32 s97, s97, 0
	global_load_dword v20, v3, s[96:97] nt
	s_add_u32 s96, s96, 0x4000
	s_addc_u32 s97, s97, 0
	global_load_dword v21, v3, s[96:97] nt
	s_add_u32 s96, s96, 0x4000
	s_addc_u32 s97, s97, 0
	global_load_dword v22, v3, s[96:97] nt
	s_add_u32 s96, s96, 0x4000
	s_addc_u32 s97, s97, 0
	global_load_dword v23, v3, s[96:97] nt
	s_add_u32 s96, s96, 0x4000
	s_addc_u32 s97, s97, 0
	global_load_dword v24, v3, s[96:97] nt
	s_add_u32 s96, s96, 0x4000
	s_addc_u32 s97, s97, 0
	global_load_dword v25, v3, s[96:97] nt
	s_add_u32 s96, s96, 0x4000
	s_addc_u32 s97, s97, 0
	global_load_dword v26, v3, s[96:97] nt
	s_add_u32 s96, s96, 0x4000
	s_addc_u32 s97, s97, 0
	global_load_dword v27, v3, s[96:97] nt
	s_add_u32 s96, s96, 0x4000
	s_addc_u32 s97, s97, 0
	global_load_dword v28, v3, s[96:97] nt
	s_add_u32 s96, s96, 0x4000
	s_addc_u32 s97, s97, 0
	global_load_dword v29, v3, s[96:97] nt
	s_add_u32 s96, s96, 0x4000
	s_addc_u32 s97, s97, 0
	global_load_dword v30, v3, s[96:97] nt
	s_add_u32 s96, s96, 0x4000
	s_addc_u32 s97, s97, 0
	global_load_dword v31, v3, s[96:97] nt
	s_add_u32 s96, s96, 0x4000
	s_addc_u32 s97, s97, 0
	global_load_dword v32, v3, s[96:97] nt
	s_add_u32 s96, s96, 0x4000
	s_addc_u32 s97, s97, 0
	global_load_dword v33, v3, s[96:97] nt
	s_add_u32 s96, s96, 0x4000
	s_addc_u32 s97, s97, 0
	global_load_dword v34, v3, s[96:97] nt
	s_add_u32 s96, s96, 0x4000
	s_addc_u32 s97, s97, 0
	global_load_dword v35, v3, s[96:97] nt
	s_add_u32 s96, s96, 0x4000
	s_addc_u32 s97, s97, 0
	global_load_dword v36, v3, s[96:97] nt
	s_add_u32 s96, s96, 0x4000
	s_addc_u32 s97, s97, 0
	global_load_dword v37, v3, s[96:97] nt
	s_add_u32 s96, s96, 0x4000
	s_addc_u32 s97, s97, 0
	global_load_dword v38, v3, s[96:97] nt
	s_add_u32 s96, s96, 0x4000
	s_addc_u32 s97, s97, 0
	global_load_dword v39, v3, s[96:97] nt
	s_add_u32 s96, s96, 0x4000
	s_addc_u32 s97, s97, 0
	global_load_dword v40, v3, s[96:97] nt
	s_add_u32 s96, s96, 0x4000
	s_addc_u32 s97, s97, 0
	global_load_dword v41, v3, s[96:97] nt
	s_add_u32 s96, s96, 0x4000
	s_addc_u32 s97, s97, 0
	global_load_dword v42, v3, s[96:97] nt
	s_add_u32 s96, s96, 0x4000
	s_addc_u32 s97, s97, 0
	global_load_dword v43, v3, s[96:97] nt
	s_add_u32 s96, s96, 0x4000
	s_addc_u32 s97, s97, 0
	global_load_dword v44, v3, s[96:97] nt
	s_add_u32 s96, s96, 0x4000
	s_addc_u32 s97, s97, 0
	global_load_dword v45, v3, s[96:97] nt
	s_add_u32 s96, s96, 0x4000
	s_addc_u32 s97, s97, 0
	global_load_dword v46, v3, s[96:97] nt
	s_add_u32 s96, s96, 0x4000
	s_addc_u32 s97, s97, 0
	global_load_dword v47, v3, s[96:97] nt
	s_mul_i32 s92, s95, 0x1000
	s_lshl_b32 s93, s91, 7
	s_add_i32 s92, s92, s93
	s_add_u32 s92, s22, s92
	s_addc_u32 s93, s23, 0
	s_add_u32 s92, s92, 0xc80000
	s_addc_u32 s93, s93, 0
	s_waitcnt vmcnt(31)
	ds_write_b32 v4, v16
	s_waitcnt vmcnt(30)
	ds_write_b32 v4, v17 offset:264
	s_waitcnt vmcnt(29)
	ds_write_b32 v4, v18 offset:528
	s_waitcnt vmcnt(28)
	ds_write_b32 v4, v19 offset:792
	s_waitcnt vmcnt(27)
	ds_write_b32 v4, v20 offset:1056
	s_waitcnt vmcnt(26)
	ds_write_b32 v4, v21 offset:1320
	s_waitcnt vmcnt(25)
	ds_write_b32 v4, v22 offset:1584
	s_waitcnt vmcnt(24)
	ds_write_b32 v4, v23 offset:1848
	s_waitcnt vmcnt(23)
	ds_write_b32 v4, v24 offset:2112
	s_waitcnt vmcnt(22)
	ds_write_b32 v4, v25 offset:2376
	s_waitcnt vmcnt(21)
	ds_write_b32 v4, v26 offset:2640
	s_waitcnt vmcnt(20)
	ds_write_b32 v4, v27 offset:2904
	s_waitcnt vmcnt(19)
	ds_write_b32 v4, v28 offset:3168
	s_waitcnt vmcnt(18)
	ds_write_b32 v4, v29 offset:3432
	s_waitcnt vmcnt(17)
	ds_write_b32 v4, v30 offset:3696
	s_waitcnt vmcnt(16)
	ds_write_b32 v4, v31 offset:3960
	s_waitcnt vmcnt(15)
	ds_write_b32 v4, v32 offset:4224
	s_waitcnt vmcnt(14)
	ds_write_b32 v4, v33 offset:4488
	s_waitcnt vmcnt(13)
	ds_write_b32 v4, v34 offset:4752
	s_waitcnt vmcnt(12)
	ds_write_b32 v4, v35 offset:5016
	s_waitcnt vmcnt(11)
	ds_write_b32 v4, v36 offset:5280
	s_waitcnt vmcnt(10)
	ds_write_b32 v4, v37 offset:5544
	s_waitcnt vmcnt(9)
	ds_write_b32 v4, v38 offset:5808
	s_waitcnt vmcnt(8)
	ds_write_b32 v4, v39 offset:6072
	s_waitcnt vmcnt(7)
	ds_write_b32 v4, v40 offset:6336
	s_waitcnt vmcnt(6)
	ds_write_b32 v4, v41 offset:6600
	s_waitcnt vmcnt(5)
	ds_write_b32 v4, v42 offset:6864
	s_waitcnt vmcnt(4)
	ds_write_b32 v4, v43 offset:7128
	s_waitcnt vmcnt(3)
	ds_write_b32 v4, v44 offset:7392
	s_waitcnt vmcnt(2)
	ds_write_b32 v4, v45 offset:7656
	s_waitcnt vmcnt(1)
	ds_write_b32 v4, v46 offset:7920
	s_waitcnt vmcnt(0)
	ds_write_b32 v4, v47 offset:8184
	s_waitcnt lgkmcnt(0)
	ds_read_b32 v48, v7
	ds_read_b32 v49, v7 offset:132
	ds_read_b32 v50, v7 offset:264
	ds_read_b32 v51, v7 offset:396
	ds_read_b32 v52, v7 offset:528
	ds_read_b32 v53, v7 offset:660
	ds_read_b32 v54, v7 offset:792
	ds_read_b32 v55, v7 offset:924
	s_waitcnt lgkmcnt(0)
	v_cvt_pk_bf16_f32 v80, v48, v49
	v_cvt_pk_bf16_f32 v81, v50, v51
	v_cvt_pk_bf16_f32 v82, v52, v53
	v_cvt_pk_bf16_f32 v83, v54, v55
	global_store_dwordx4 v8, v[80:83], s[92:93]
	ds_read_b32 v56, v7 offset:32
	ds_read_b32 v57, v7 offset:164
	ds_read_b32 v58, v7 offset:296
	ds_read_b32 v59, v7 offset:428
	ds_read_b32 v60, v7 offset:560
	ds_read_b32 v61, v7 offset:692
	ds_read_b32 v62, v7 offset:824
	ds_read_b32 v63, v7 offset:956
	s_waitcnt lgkmcnt(0)
	v_cvt_pk_bf16_f32 v84, v56, v57
	v_cvt_pk_bf16_f32 v85, v58, v59
	v_cvt_pk_bf16_f32 v86, v60, v61
	v_cvt_pk_bf16_f32 v87, v62, v63
	global_store_dwordx4 v9, v[84:87], s[92:93]
	ds_read_b32 v64, v7 offset:64
	ds_read_b32 v65, v7 offset:196
	ds_read_b32 v66, v7 offset:328
	ds_read_b32 v67, v7 offset:460
	ds_read_b32 v68, v7 offset:592
	ds_read_b32 v69, v7 offset:724
	ds_read_b32 v70, v7 offset:856
	ds_read_b32 v71, v7 offset:988
	s_waitcnt lgkmcnt(0)
	v_cvt_pk_bf16_f32 v88, v64, v65
	v_cvt_pk_bf16_f32 v89, v66, v67
	v_cvt_pk_bf16_f32 v90, v68, v69
	v_cvt_pk_bf16_f32 v91, v70, v71
	global_store_dwordx4 v10, v[88:91], s[92:93]
	ds_read_b32 v72, v7 offset:96
	ds_read_b32 v73, v7 offset:228
	ds_read_b32 v74, v7 offset:360
	ds_read_b32 v75, v7 offset:492
	ds_read_b32 v76, v7 offset:624
	ds_read_b32 v77, v7 offset:756
	ds_read_b32 v78, v7 offset:888
	ds_read_b32 v79, v7 offset:1020
	s_waitcnt lgkmcnt(0)
	v_cvt_pk_bf16_f32 v92, v72, v73
	v_cvt_pk_bf16_f32 v93, v74, v75
	v_cvt_pk_bf16_f32 v94, v76, v77
	v_cvt_pk_bf16_f32 v95, v78, v79
	global_store_dwordx4 v11, v[92:95], s[92:93]
	s_add_i32 s85, s85, 0xa00
	s_branch .Lgconv_wo_loop

; __device__ __forceinline__ void convert_items(const Params& p, LAS float* scr, int lane, int gw, int NGW, int it_lo, int it_hi) {
;     ...
;     for (int it = it_lo + gw; it < it_hi; it += NGW) {
;         int r = it;
;         if (r < CV_WIN) { const int kb = r / 417, nb = r % 417, ns = nb * 32; const int nd = ns < 9216 ? ns : (ns < 9248 ? 13312 + (ns - 9216) : ns - 32);
;             transpose_item(p.in[8], IN_COLS, 2048, (bf16_t*)(ws + WS_WIN), kb * 64, ns, nd, scr, lane); continue; } r -= CV_WIN;
;         if (r < CV_POOL) { const int g = r / 32, q = r % 32, kb = q / 8, nb = q % 8;
;             transpose_item(p.in[9] + g * 65536, 256, 256, (bf16_t*)(ws + WS_WPOOL) + g * 65536, kb * 64, nb * 32, nb * 32, scr, lane); continue; } r -= CV_POOL;
;         if (r < CV_WPU) { const int kb = r / 64, nb = r % 64; transpose_item(p.in[15], 2048, 1024, (bf16_t*)(ws + WS_WPU), kb * 64, nb * 32, nb * 32, scr, lane); continue; } r -= CV_WPU;
;         if (r < CV_2K) { const int kb = r / 64, nb = r % 64; transpose_item(p.in[16], 2048, 2048, (bf16_t*)(ws + WS_WGU), kb * 64, nb * 32, nb * 32, scr, lane); continue; } r -= CV_2K;
.Lgconv_wo_done:
	s_mov_b64 exec, -1
	v_mbcnt_lo_u32_b32 v0, -1, 0
	v_mbcnt_hi_u32_b32 v0, -1, v0
	s_lshr_b32 s84, s24, 6
	s_cmp_gt_u32 s2, 0xbf
	s_cbranch_scc1 .Lgconv_wgu_hi
	s_sub_i32 s85, s2, 64
	s_lshl_b32 s85, s85, 3
	s_add_i32 s85, s85, s84
	s_mul_i32 s88, s85, 1
	s_add_i32 s89, s88, 1
	s_branch .Lgconv_wgu_slots

; #define LAS __attribute__((address_space(3)))
; __device__ __forceinline__ unsigned pk2(float lo, float hi) { const f32x2_t v = {lo, hi}; const bf16x2_t b = __builtin_convertvector(v, bf16x2_t); return __builtin_bit_cast(unsigned, b); }
; #define LDS_WAIT() asm volatile("s_waitcnt lgkmcnt(0)" ::: "memory")
; __device__ __forceinline__ void transpose_item(const float* W, int N, int K, bf16_t* WT, int k0, int n0src, int n0dst, LAS float* scr, int lane) {
;     float tv[32];
; #pragma unroll
;     for (int i = 0; i < 32; ++i) tv[i] = __builtin_nontemporal_load(&W[(size_t)(k0 + 2 * i + (lane >> 5)) * N + n0src + (lane & 31)]);
; #pragma unroll
;     for (int i = 0; i < 32; ++i) scr[(2 * i + (lane >> 5)) * 33 + (lane & 31)] = tv[i];
;     LDS_WAIT();
;     const int c = lane & 7;
; #pragma unroll
;     for (int j = 0; j < 4; ++j) { const int n = (lane >> 3) + 8 * j; const LAS float* s = scr + (8 * c) * 33 + n;
;         u32x4 o; o.x = pk2(s[0 * 33], s[1 * 33]); o.y = pk2(s[2 * 33], s[3 * 33]); o.z = pk2(s[4 * 33], s[5 * 33]); o.w = pk2(s[6 * 33], s[7 * 33]);
;         *(u32x4*)(WT + (size_t)(n0dst + n) * K + k0 + 8 * c) = o; }
; __device__ __forceinline__ void convert_items(const Params& p, LAS float* scr, int lane, int gw, int NGW, int it_lo, int it_hi) {
;     ...
;         if (r < CV_2K) { const int kb = r / 64, nb = r % 64; transpose_item(p.in[16], 2048, 2048, (bf16_t*)(ws + WS_WGU), kb * 64, nb * 32, nb * 32, scr, lane); continue; } r -= CV_2K;
.Lgconv_wgu_slots:
	s_add_i32 s85, s88, 0x800
	s_sub_i32 s91, s85, 0xa00
	s_cmp_ge_u32 s85, 0xa00
	s_cselect_b32 s85, s91, s85
	v_readlane_b32 s86, v254, 0
	v_readlane_b32 s87, v254, 1
	s_mul_i32 s90, s84, 0x2100
	v_lshrrev_b32_e32 v1, 5, v0
	v_and_b32_e32 v2, 31, v0
	v_mul_u32_u24_e32 v3, 0x2000, v1
	v_lshl_add_u32 v3, v2, 2, v3
	v_mul_u32_u24_e32 v4, 33, v1
	v_add_u32_e32 v4, v4, v2
	v_lshl_add_u32 v4, v4, 2, s90
	v_and_b32_e32 v5, 7, v0
	v_lshrrev_b32_e32 v6, 3, v0
	v_mul_u32_u24_e32 v7, 0x420, v5
	v_lshl_add_u32 v7, v6, 2, v7
	v_add_u32_e32 v7, s90, v7
	v_mul_u32_u24_e32 v8, 0x1000, v6
	v_lshl_add_u32 v8, v5, 4, v8
	v_add_u32_e32 v9, 0x8000, v8
	v_add_u32_e32 v10, 0x10000, v8
	v_add_u32_e32 v11, 0x18000, v8
; #define LAS __attribute__((address_space(3)))
; __device__ __forceinline__ unsigned pk2(float lo, float hi) { const f32x2_t v = {lo, hi}; const bf16x2_t b = __builtin_convertvector(v, bf16x2_t); return __builtin_bit_cast(unsigned, b); }
; #define LDS_WAIT() asm volatile("s_waitcnt lgkmcnt(0)" ::: "memory")
; __device__ __forceinline__ void transpose_item(const float* W, int N, int K, bf16_t* WT, int k0, int n0src, int n0dst, LAS float* scr, int lane) {
;     float tv[32];
; #pragma unroll
;     for (int i = 0; i < 32; ++i) tv[i] = __builtin_nontemporal_load(&W[(size_t)(k0 + 2 * i + (lane >> 5)) * N + n0src + (lane & 31)]);
; #pragma unroll
;     for (int i = 0; i < 32; ++i) scr[(2 * i + (lane >> 5)) * 33 + (lane & 31)] = tv[i];
;     LDS_WAIT();
;     const int c = lane & 7;
; #pragma unroll
;     for (int j = 0; j < 4; ++j) { const int n = (lane >> 3) + 8 * j; const LAS float* s = scr + (8 * c) * 33 + n;
;         u32x4 o; o.x = pk2(s[0 * 33], s[1 * 33]); o.y = pk2(s[2 * 33], s[3 * 33]); o.z = pk2(s[4 * 33], s[5 * 33]); o.w = pk2(s[6 * 33], s[7 * 33]);
;         *(u32x4*)(WT + (size_t)(n0dst + n) * K + k0 + 8 * c) = o; }
;     LDS_WAIT();
; __device__ __forceinline__ void convert_items(const Params& p, LAS float* scr, int lane, int gw, int NGW, int it_lo, int it_hi) {
;     ...
;         if (r < CV_2K) { const int kb = r / 64, nb = r % 64; transpose_item(p.in[16], 2048, 2048, (bf16_t*)(ws + WS_WGU), kb * 64, nb * 32, nb * 32, scr, lane); continue; } r -= CV_2K;
.Lgconv_wgu_loop:
	s_cmp_lt_u32 s85, 0x800
	s_cbranch_scc0 .Lgconv_wgu_next
	s_lshr_b32 s91, s85, 6
	s_mul_i32 s92, s91, 0x40
	s_sub_i32 s92, s85, s92
	s_lshl_b32 s92, s92, 5
	s_mov_b32 s95, s92
	s_mul_i32 s96, s91, 0x80000
	s_lshl_b32 s97, s92, 2
	s_add_i32 s96, s96, s97
	s_add_u32 s96, s86, s96
	s_addc_u32 s97, s87, 0
	global_load_dword v16, v3, s[96:97] nt
	s_add_u32 s96, s96, 0x4000
	s_addc_u32 s97, s97, 0
	global_load_dword v17, v3, s[96:97] nt
	s_add_u32 s96, s96, 0x4000
	s_addc_u32 s97, s97, 0
	global_load_dword v18, v3, s[96:97] nt
	s_add_u32 s96, s96, 0x4000
	s_addc_u32 s97, s97, 0
	global_load_dword v19, v3, s[96:97] nt
	s_add_u32 s96, s96, 0x4000
	s_addc_u32 s97, s97, 0
	global_load_dword v20, v3, s[96:97] nt
	s_add_u32 s96, s96, 0x4000
	s_addc_u32 s97, s97, 0
	global_load_dword v21, v3, s[96:97] nt
	s_add_u32 s96, s96, 0x4000
	s_addc_u32 s97, s97, 0
	global_load_dword v22, v3, s[96:97] nt
	s_add_u32 s96, s96, 0x4000
	s_addc_u32 s97, s97, 0
	global_load_dword v23, v3, s[96:97] nt
	s_add_u32 s96, s96, 0x4000
	s_addc_u32 s97, s97, 0
	global_load_dword v24, v3, s[96:97] nt
	s_add_u32 s96, s96, 0x4000
	s_addc_u32 s97, s97, 0
	global_load_dword v25, v3, s[96:97] nt
	s_add_u32 s96, s96, 0x4000
	s_addc_u32 s97, s97, 0
	global_load_dword v26, v3, s[96:97] nt
	s_add_u32 s96, s96, 0x4000
	s_addc_u32 s97, s97, 0
	global_load_dword v27, v3, s[96:97] nt
	s_add_u32 s96, s96, 0x4000
	s_addc_u32 s97, s97, 0
	global_load_dword v28, v3, s[96:97] nt
	s_add_u32 s96, s96, 0x4000
	s_addc_u32 s97, s97, 0
	global_load_dword v29, v3, s[96:97] nt
	s_add_u32 s96, s96, 0x4000
	s_addc_u32 s97, s97, 0
	global_load_dword v30, v3, s[96:97] nt
	s_add_u32 s96, s96, 0x4000
	s_addc_u32 s97, s97, 0
	global_load_dword v31, v3, s[96:97] nt
	s_add_u32 s96, s96, 0x4000
	s_addc_u32 s97, s97, 0
	global_load_dword v32, v3, s[96:97] nt
	s_add_u32 s96, s96, 0x4000
	s_addc_u32 s97, s97, 0
	global_load_dword v33, v3, s[96:97] nt
	s_add_u32 s96, s96, 0x4000
	s_addc_u32 s97, s97, 0
	global_load_dword v34, v3, s[96:97] nt
	s_add_u32 s96, s96, 0x4000
	s_addc_u32 s97, s97, 0
	global_load_dword v35, v3, s[96:97] nt
	s_add_u32 s96, s96, 0x4000
	s_addc_u32 s97, s97, 0
	global_load_dword v36, v3, s[96:97] nt
	s_add_u32 s96, s96, 0x4000
	s_addc_u32 s97, s97, 0
	global_load_dword v37, v3, s[96:97] nt
	s_add_u32 s96, s96, 0x4000
	s_addc_u32 s97, s97, 0
	global_load_dword v38, v3, s[96:97] nt
	s_add_u32 s96, s96, 0x4000
	s_addc_u32 s97, s97, 0
	global_load_dword v39, v3, s[96:97] nt
	s_add_u32 s96, s96, 0x4000
	s_addc_u32 s97, s97, 0
	global_load_dword v40, v3, s[96:97] nt
	s_add_u32 s96, s96, 0x4000
	s_addc_u32 s97, s97, 0
	global_load_dword v41, v3, s[96:97] nt
	s_add_u32 s96, s96, 0x4000
	s_addc_u32 s97, s97, 0
	global_load_dword v42, v3, s[96:97] nt
	s_add_u32 s96, s96, 0x4000
	s_addc_u32 s97, s97, 0
	global_load_dword v43, v3, s[96:97] nt
	s_add_u32 s96, s96, 0x4000
	s_addc_u32 s97, s97, 0
	global_load_dword v44, v3, s[96:97] nt
	s_add_u32 s96, s96, 0x4000
	s_addc_u32 s97, s97, 0
	global_load_dword v45, v3, s[96:97] nt
	s_add_u32 s96, s96, 0x4000
	s_addc_u32 s97, s97, 0
	global_load_dword v46, v3, s[96:97] nt
	s_add_u32 s96, s96, 0x4000
	s_addc_u32 s97, s97, 0
	global_load_dword v47, v3, s[96:97] nt
	s_mul_i32 s92, s95, 0x1000
	s_lshl_b32 s93, s91, 7
	s_add_i32 s92, s92, s93
	s_add_u32 s92, s22, s92
	s_addc_u32 s93, s23, 0
	s_add_u32 s92, s92, 0x480000
	s_addc_u32 s93, s93, 0
	s_waitcnt vmcnt(31)
	ds_write_b32 v4, v16
	s_waitcnt vmcnt(30)
	ds_write_b32 v4, v17 offset:264
	s_waitcnt vmcnt(29)
	ds_write_b32 v4, v18 offset:528
	s_waitcnt vmcnt(28)
	ds_write_b32 v4, v19 offset:792
	s_waitcnt vmcnt(27)
	ds_write_b32 v4, v20 offset:1056
	s_waitcnt vmcnt(26)
	ds_write_b32 v4, v21 offset:1320
	s_waitcnt vmcnt(25)
	ds_write_b32 v4, v22 offset:1584
	s_waitcnt vmcnt(24)
	ds_write_b32 v4, v23 offset:1848
	s_waitcnt vmcnt(23)
	ds_write_b32 v4, v24 offset:2112
	s_waitcnt vmcnt(22)
	ds_write_b32 v4, v25 offset:2376
	s_waitcnt vmcnt(21)
	ds_write_b32 v4, v26 offset:2640
	s_waitcnt vmcnt(20)
	ds_write_b32 v4, v27 offset:2904
	s_waitcnt vmcnt(19)
	ds_write_b32 v4, v28 offset:3168
	s_waitcnt vmcnt(18)
	ds_write_b32 v4, v29 offset:3432
	s_waitcnt vmcnt(17)
	ds_write_b32 v4, v30 offset:3696
	s_waitcnt vmcnt(16)
	ds_write_b32 v4, v31 offset:3960
	s_waitcnt vmcnt(15)
	ds_write_b32 v4, v32 offset:4224
	s_waitcnt vmcnt(14)
	ds_write_b32 v4, v33 offset:4488
	s_waitcnt vmcnt(13)
	ds_write_b32 v4, v34 offset:4752
	s_waitcnt vmcnt(12)
	ds_write_b32 v4, v35 offset:5016
	s_waitcnt vmcnt(11)
	ds_write_b32 v4, v36 offset:5280
	s_waitcnt vmcnt(10)
	ds_write_b32 v4, v37 offset:5544
	s_waitcnt vmcnt(9)
	ds_write_b32 v4, v38 offset:5808
	s_waitcnt vmcnt(8)
	ds_write_b32 v4, v39 offset:6072
	s_waitcnt vmcnt(7)
	ds_write_b32 v4, v40 offset:6336
	s_waitcnt vmcnt(6)
	ds_write_b32 v4, v41 offset:6600
	s_waitcnt vmcnt(5)
	ds_write_b32 v4, v42 offset:6864
	s_waitcnt vmcnt(4)
	ds_write_b32 v4, v43 offset:7128
	s_waitcnt vmcnt(3)
	ds_write_b32 v4, v44 offset:7392
	s_waitcnt vmcnt(2)
	ds_write_b32 v4, v45 offset:7656
	s_waitcnt vmcnt(1)
	ds_write_b32 v4, v46 offset:7920
	s_waitcnt vmcnt(0)
	ds_write_b32 v4, v47 offset:8184
	s_waitcnt lgkmcnt(0)
	ds_read_b32 v48, v7
	ds_read_b32 v49, v7 offset:132
	ds_read_b32 v50, v7 offset:264
	ds_read_b32 v51, v7 offset:396
	ds_read_b32 v52, v7 offset:528
	ds_read_b32 v53, v7 offset:660
	ds_read_b32 v54, v7 offset:792
	ds_read_b32 v55, v7 offset:924
	s_waitcnt lgkmcnt(0)
	v_cvt_pk_bf16_f32 v80, v48, v49
	v_cvt_pk_bf16_f32 v81, v50, v51
	v_cvt_pk_bf16_f32 v82, v52, v53
	v_cvt_pk_bf16_f32 v83, v54, v55
	global_store_dwordx4 v8, v[80:83], s[92:93]
	ds_read_b32 v56, v7 offset:32
	ds_read_b32 v57, v7 offset:164
	ds_read_b32 v58, v7 offset:296
	ds_read_b32 v59, v7 offset:428
	ds_read_b32 v60, v7 offset:560
	ds_read_b32 v61, v7 offset:692
	ds_read_b32 v62, v7 offset:824
	ds_read_b32 v63, v7 offset:956
	s_waitcnt lgkmcnt(0)
	v_cvt_pk_bf16_f32 v84, v56, v57
	v_cvt_pk_bf16_f32 v85, v58, v59
	v_cvt_pk_bf16_f32 v86, v60, v61
	v_cvt_pk_bf16_f32 v87, v62, v63
	global_store_dwordx4 v9, v[84:87], s[92:93]
	ds_read_b32 v64, v7 offset:64
	ds_read_b32 v65, v7 offset:196
	ds_read_b32 v66, v7 offset:328
	ds_read_b32 v67, v7 offset:460
	ds_read_b32 v68, v7 offset:592
	ds_read_b32 v69, v7 offset:724
	ds_read_b32 v70, v7 offset:856
	ds_read_b32 v71, v7 offset:988
	s_waitcnt lgkmcnt(0)
	v_cvt_pk_bf16_f32 v88, v64, v65
	v_cvt_pk_bf16_f32 v89, v66, v67
	v_cvt_pk_bf16_f32 v90, v68, v69
	v_cvt_pk_bf16_f32 v91, v70, v71
	global_store_dwordx4 v10, v[88:91], s[92:93]
	ds_read_b32 v72, v7 offset:96
	ds_read_b32 v73, v7 offset:228
	ds_read_b32 v74, v7 offset:360
	ds_read_b32 v75, v7 offset:492
	ds_read_b32 v76, v7 offset:624
	ds_read_b32 v77, v7 offset:756
	ds_read_b32 v78, v7 offset:888
	ds_read_b32 v79, v7 offset:1020
	s_waitcnt lgkmcnt(0)
	v_cvt_pk_bf16_f32 v92, v72, v73
	v_cvt_pk_bf16_f32 v93, v74, v75
	v_cvt_pk_bf16_f32 v94, v76, v77
	v_cvt_pk_bf16_f32 v95, v78, v79
	global_store_dwordx4 v11, v[92:95], s[92:93]
	s_add_i32 s85, s85, 0xa00
	s_branch .Lgconv_wgu_loop
